# v7 + nt (streaming) policy on the once-written f32 output stores of the memory K/V epilogue and the final RMSNorm
# baseline (speedup 1.0000x reference)
; __device__ __forceinline__ u32x4 pack8(f32x4 a, f32x4 b) { u32x4 w; w.x = cvt_pk_bf16(a[0], a[1]); w.y = cvt_pk_bf16(a[2], a[3]); w.z = cvt_pk_bf16(b[0], b[1]); w.w = cvt_pk_bf16(b[2], b[3]); return w; }
;     __device__ __forceinline__ void operator()(const f32x4 (&acc)[2][2][4][2], const Unit& u, int wr, int wc, int fr_, int fq_) const {
;         int fr = fr_, fq = fq_; asm volatile("" : "+v"(fr), "+v"(fq));
;         const int layer = u.pn >> 3, isv = (u.pn >> 2) & 1, cw = (u.pn & 3) * 256 + wc * 32 + 8 * fq;
;         float* of = (isv ? outv : outk) + (size_t)layer * MMEM * D; bf16_t* ob = (isv ? vb : kb) + (size_t)layer * MMEM * D;
; #pragma unroll
;         for (int ai = 0; ai < 2; ++ai)
; #pragma unroll
;             for (int m = 0; m < 4; ++m) {
;                 const int row = u.pm * 256 + ai * 128 + wr * 64 + m * 16 + fr;
;                 const float rs = rstdm[row];
; #pragma unroll
;                 for (int bj = 0; bj < 2; ++bj) {
;                     const size_t off = (size_t)row * D + bj * 128 + cw;
;                     const f32x4 v0 = acc[ai][bj][m][0] * rs, v1 = acc[ai][bj][m][1] * rs;
;                     *(f32x4*)(of + off) = v0; *(f32x4*)(of + off + 4) = v1;
;                     *(u32x4*)(ob + off) = pack8(v0, v1);
;                 }
;             }
;     }
.LBB0_393:
	s_lshl_b32 s21, s28, 8
	s_add_i32 s21, s21, s49
	v_mov_b32_e32 v155, v149
	v_mov_b32_e32 v144, v148
	s_ashr_i32 s30, s29, 3
	v_add_u32_e32 v146, s21, v144
	v_ashrrev_i32_e32 v147, 31, v146
	v_lshl_add_u64 v[144:145], v[146:147], 2, s[14:15]
	global_load_dword v154, v[144:145], off
	s_lshl_b32 s21, s29, 8
	s_and_b32 s21, s21, 0x300
	s_and_b32 s23, s29, 4
	s_ashr_i32 s31, s30, 31
	s_or_b32 s21, s21, s50
	s_cmp_eq_u32 s23, 0
	v_lshl_add_u32 v144, v155, 3, s21
	s_cselect_b32 s21, s57, 0x75b0000
	s_cselect_b32 s23, s58, 0x1a000000
	s_add_u32 s21, s8, s21
	s_addc_u32 s34, s9, 0
	s_lshl_b64 s[28:29], s[30:31], 23
	s_add_u32 s28, s21, s28
	s_addc_u32 s29, s34, s29
	s_add_u32 s21, s10, s23
	v_ashrrev_i32_e32 v145, 31, v144
	v_lshlrev_b64 v[158:159], 10, v[146:147]
	s_addc_u32 s23, s11, 0
	s_lshl_b64 s[30:31], s[30:31], 22
	v_lshl_add_u64 v[158:159], v[158:159], 0, v[144:145]
	s_add_u32 s30, s21, s30
	v_add_u32_e32 v156, 16, v146
	v_lshl_add_u64 v[162:163], v[158:159], 2, s[28:29]
	s_addc_u32 s31, s23, s31
	v_ashrrev_i32_e32 v157, 31, v156
	v_lshl_add_u64 v[158:159], v[158:159], 1, s[30:31]
	v_lshl_add_u64 v[160:161], v[156:157], 2, s[14:15]
	s_andn2_b64 vcc, exec, s[4:5]
	s_mov_b64 s[4:5], -1
	s_waitcnt vmcnt(0)
	v_pk_mul_f32 v[126:127], v[126:127], v[154:155] op_sel_hi:[1,0]
	v_pk_mul_f32 v[124:125], v[124:125], v[154:155] op_sel_hi:[1,0]
	v_pk_mul_f32 v[122:123], v[122:123], v[154:155] op_sel_hi:[1,0]
	v_pk_mul_f32 v[120:121], v[120:121], v[154:155] op_sel_hi:[1,0]
	v_pk_mul_f32 v[118:119], v[118:119], v[154:155] op_sel_hi:[1,0]
	v_pk_mul_f32 v[116:117], v[116:117], v[154:155] op_sel_hi:[1,0]
	v_pk_mul_f32 v[114:115], v[114:115], v[154:155] op_sel_hi:[1,0]
	v_pk_mul_f32 v[112:113], v[112:113], v[154:155] op_sel_hi:[1,0]
	global_store_dwordx4 v[162:163], v[124:127], off nt
	global_store_dwordx4 v[162:163], v[120:123], off offset:16 nt
	s_nop 0
	v_cvt_pk_bf16_f32 v124, v124, v125
	v_cvt_pk_bf16_f32 v125, v126, v127
	v_cvt_pk_bf16_f32 v126, v120, v121
	v_cvt_pk_bf16_f32 v127, v122, v123
	v_cvt_pk_bf16_f32 v120, v116, v117
	v_cvt_pk_bf16_f32 v121, v118, v119
	v_cvt_pk_bf16_f32 v122, v112, v113
	v_cvt_pk_bf16_f32 v123, v114, v115
	global_store_dwordx4 v[158:159], v[124:127], off
	global_store_dwordx4 v[162:163], v[116:119], off offset:512 nt
	global_store_dwordx4 v[162:163], v[112:115], off offset:528 nt
	global_store_dwordx4 v[158:159], v[120:123], off offset:256
	global_load_dword v112, v[160:161], off
	v_lshlrev_b64 v[116:117], 10, v[156:157]
	v_lshl_add_u64 v[116:117], v[116:117], 0, v[144:145]
	v_add_u32_e32 v114, 32, v146
	v_lshl_add_u64 v[120:121], v[116:117], 2, s[28:29]
	v_ashrrev_i32_e32 v115, 31, v114
	v_lshl_add_u64 v[116:117], v[116:117], 1, s[30:31]
	v_lshl_add_u64 v[118:119], v[114:115], 2, s[14:15]
	s_waitcnt vmcnt(0)
	v_pk_mul_f32 v[110:111], v[110:111], v[112:113] op_sel_hi:[1,0]
	v_pk_mul_f32 v[108:109], v[108:109], v[112:113] op_sel_hi:[1,0]
	v_pk_mul_f32 v[106:107], v[106:107], v[112:113] op_sel_hi:[1,0]
	v_pk_mul_f32 v[104:105], v[104:105], v[112:113] op_sel_hi:[1,0]
	v_pk_mul_f32 v[102:103], v[102:103], v[112:113] op_sel_hi:[1,0]
	v_pk_mul_f32 v[100:101], v[100:101], v[112:113] op_sel_hi:[1,0]
	v_pk_mul_f32 v[98:99], v[98:99], v[112:113] op_sel_hi:[1,0]
	v_pk_mul_f32 v[96:97], v[96:97], v[112:113] op_sel_hi:[1,0]
	global_store_dwordx4 v[120:121], v[108:111], off nt
	global_store_dwordx4 v[120:121], v[104:107], off offset:16 nt
	s_nop 0
	v_cvt_pk_bf16_f32 v108, v108, v109
	v_cvt_pk_bf16_f32 v109, v110, v111
	v_cvt_pk_bf16_f32 v110, v104, v105
	v_cvt_pk_bf16_f32 v111, v106, v107
	v_cvt_pk_bf16_f32 v104, v100, v101
	v_cvt_pk_bf16_f32 v105, v102, v103
	v_cvt_pk_bf16_f32 v106, v96, v97
	v_cvt_pk_bf16_f32 v107, v98, v99
	global_store_dwordx4 v[116:117], v[108:111], off
	global_store_dwordx4 v[120:121], v[100:103], off offset:512 nt
	global_store_dwordx4 v[120:121], v[96:99], off offset:528 nt
	global_store_dwordx4 v[116:117], v[104:107], off offset:256
	global_load_dword v96, v[118:119], off
	v_lshlrev_b64 v[100:101], 10, v[114:115]
	v_lshl_add_u64 v[100:101], v[100:101], 0, v[144:145]
	v_add_u32_e32 v98, 48, v146
	v_lshl_add_u64 v[104:105], v[100:101], 2, s[28:29]
	v_ashrrev_i32_e32 v99, 31, v98
	v_lshl_add_u64 v[100:101], v[100:101], 1, s[30:31]
	v_lshl_add_u64 v[102:103], v[98:99], 2, s[14:15]
	s_waitcnt vmcnt(0)
	v_pk_mul_f32 v[94:95], v[94:95], v[96:97] op_sel_hi:[1,0]
	v_pk_mul_f32 v[92:93], v[92:93], v[96:97] op_sel_hi:[1,0]
	v_pk_mul_f32 v[90:91], v[90:91], v[96:97] op_sel_hi:[1,0]
	v_pk_mul_f32 v[88:89], v[88:89], v[96:97] op_sel_hi:[1,0]
	v_pk_mul_f32 v[86:87], v[86:87], v[96:97] op_sel_hi:[1,0]
	v_pk_mul_f32 v[84:85], v[84:85], v[96:97] op_sel_hi:[1,0]
	v_pk_mul_f32 v[82:83], v[82:83], v[96:97] op_sel_hi:[1,0]
	v_pk_mul_f32 v[80:81], v[80:81], v[96:97] op_sel_hi:[1,0]
	global_store_dwordx4 v[104:105], v[92:95], off nt
	global_store_dwordx4 v[104:105], v[88:91], off offset:16 nt
	s_nop 0
	v_cvt_pk_bf16_f32 v92, v92, v93
	v_cvt_pk_bf16_f32 v93, v94, v95
	v_cvt_pk_bf16_f32 v94, v88, v89
	v_cvt_pk_bf16_f32 v95, v90, v91
	v_cvt_pk_bf16_f32 v88, v84, v85
	v_cvt_pk_bf16_f32 v89, v86, v87
	v_cvt_pk_bf16_f32 v90, v80, v81
	v_cvt_pk_bf16_f32 v91, v82, v83
	global_store_dwordx4 v[100:101], v[92:95], off
	global_store_dwordx4 v[104:105], v[84:87], off offset:512 nt
	global_store_dwordx4 v[104:105], v[80:83], off offset:528 nt
	global_store_dwordx4 v[100:101], v[88:91], off offset:256
	global_load_dword v80, v[102:103], off
	v_lshlrev_b64 v[84:85], 10, v[98:99]
	v_lshl_add_u64 v[84:85], v[84:85], 0, v[144:145]
	v_add_u32_e32 v82, 0x80, v146
	v_lshl_add_u64 v[88:89], v[84:85], 2, s[28:29]
	v_ashrrev_i32_e32 v83, 31, v82
	v_lshl_add_u64 v[84:85], v[84:85], 1, s[30:31]
	v_lshl_add_u64 v[86:87], v[82:83], 2, s[14:15]
	s_waitcnt vmcnt(0)
; __device__ __forceinline__ u32x4 pack8(f32x4 a, f32x4 b) { u32x4 w; w.x = cvt_pk_bf16(a[0], a[1]); w.y = cvt_pk_bf16(a[2], a[3]); w.z = cvt_pk_bf16(b[0], b[1]); w.w = cvt_pk_bf16(b[2], b[3]); return w; }
;     __device__ __forceinline__ void operator()(const f32x4 (&acc)[2][2][4][2], const Unit& u, int wr, int wc, int fr_, int fq_) const {
;         int fr = fr_, fq = fq_; asm volatile("" : "+v"(fr), "+v"(fq));
;         const int layer = u.pn >> 3, isv = (u.pn >> 2) & 1, cw = (u.pn & 3) * 256 + wc * 32 + 8 * fq;
;         float* of = (isv ? outv : outk) + (size_t)layer * MMEM * D; bf16_t* ob = (isv ? vb : kb) + (size_t)layer * MMEM * D;
; #pragma unroll
;         for (int ai = 0; ai < 2; ++ai)
; #pragma unroll
;             for (int m = 0; m < 4; ++m) {
;                 const int row = u.pm * 256 + ai * 128 + wr * 64 + m * 16 + fr;
;                 const float rs = rstdm[row];
; #pragma unroll
;                 for (int bj = 0; bj < 2; ++bj) {
;                     const size_t off = (size_t)row * D + bj * 128 + cw;
;                     const f32x4 v0 = acc[ai][bj][m][0] * rs, v1 = acc[ai][bj][m][1] * rs;
;                     *(f32x4*)(of + off) = v0; *(f32x4*)(of + off + 4) = v1;
;                     *(u32x4*)(ob + off) = pack8(v0, v1);
;                 }
;             }
;     }
	v_pk_mul_f32 v[78:79], v[78:79], v[80:81] op_sel_hi:[1,0]
	v_pk_mul_f32 v[76:77], v[76:77], v[80:81] op_sel_hi:[1,0]
	v_pk_mul_f32 v[74:75], v[74:75], v[80:81] op_sel_hi:[1,0]
	v_pk_mul_f32 v[72:73], v[72:73], v[80:81] op_sel_hi:[1,0]
	v_pk_mul_f32 v[70:71], v[70:71], v[80:81] op_sel_hi:[1,0]
	v_pk_mul_f32 v[68:69], v[68:69], v[80:81] op_sel_hi:[1,0]
	v_pk_mul_f32 v[66:67], v[66:67], v[80:81] op_sel_hi:[1,0]
	v_pk_mul_f32 v[64:65], v[64:65], v[80:81] op_sel_hi:[1,0]
	global_store_dwordx4 v[88:89], v[76:79], off nt
	global_store_dwordx4 v[88:89], v[72:75], off offset:16 nt
	s_nop 0
	v_cvt_pk_bf16_f32 v76, v76, v77
	v_cvt_pk_bf16_f32 v77, v78, v79
	v_cvt_pk_bf16_f32 v78, v72, v73
	v_cvt_pk_bf16_f32 v79, v74, v75
	v_cvt_pk_bf16_f32 v72, v68, v69
	v_cvt_pk_bf16_f32 v73, v70, v71
	v_cvt_pk_bf16_f32 v74, v64, v65
	v_cvt_pk_bf16_f32 v75, v66, v67
	global_store_dwordx4 v[84:85], v[76:79], off
	global_store_dwordx4 v[88:89], v[68:71], off offset:512 nt
	global_store_dwordx4 v[88:89], v[64:67], off offset:528 nt
	global_store_dwordx4 v[84:85], v[72:75], off offset:256
	global_load_dword v64, v[86:87], off
	v_lshlrev_b64 v[68:69], 10, v[82:83]
	v_lshl_add_u64 v[68:69], v[68:69], 0, v[144:145]
	v_add_u32_e32 v66, 0x90, v146
	v_lshl_add_u64 v[72:73], v[68:69], 2, s[28:29]
	v_ashrrev_i32_e32 v67, 31, v66
	v_lshl_add_u64 v[68:69], v[68:69], 1, s[30:31]
	v_lshl_add_u64 v[70:71], v[66:67], 2, s[14:15]
	s_waitcnt vmcnt(0)
	v_pk_mul_f32 v[62:63], v[62:63], v[64:65] op_sel_hi:[1,0]
	v_pk_mul_f32 v[60:61], v[60:61], v[64:65] op_sel_hi:[1,0]
	v_pk_mul_f32 v[58:59], v[58:59], v[64:65] op_sel_hi:[1,0]
	v_pk_mul_f32 v[56:57], v[56:57], v[64:65] op_sel_hi:[1,0]
	v_pk_mul_f32 v[54:55], v[54:55], v[64:65] op_sel_hi:[1,0]
	v_pk_mul_f32 v[52:53], v[52:53], v[64:65] op_sel_hi:[1,0]
	v_pk_mul_f32 v[50:51], v[50:51], v[64:65] op_sel_hi:[1,0]
	v_pk_mul_f32 v[48:49], v[48:49], v[64:65] op_sel_hi:[1,0]
	global_store_dwordx4 v[72:73], v[60:63], off nt
	global_store_dwordx4 v[72:73], v[56:59], off offset:16 nt
	s_nop 0
	v_cvt_pk_bf16_f32 v60, v60, v61
	v_cvt_pk_bf16_f32 v61, v62, v63
	v_cvt_pk_bf16_f32 v62, v56, v57
	v_cvt_pk_bf16_f32 v63, v58, v59
	v_cvt_pk_bf16_f32 v56, v52, v53
	v_cvt_pk_bf16_f32 v57, v54, v55
	v_cvt_pk_bf16_f32 v58, v48, v49
	v_cvt_pk_bf16_f32 v59, v50, v51
	global_store_dwordx4 v[68:69], v[60:63], off
	global_store_dwordx4 v[72:73], v[52:55], off offset:512 nt
	global_store_dwordx4 v[72:73], v[48:51], off offset:528 nt
	global_store_dwordx4 v[68:69], v[56:59], off offset:256
	global_load_dword v48, v[70:71], off
	v_lshlrev_b64 v[52:53], 10, v[66:67]
	v_lshl_add_u64 v[52:53], v[52:53], 0, v[144:145]
	v_add_u32_e32 v50, 0xa0, v146
	v_lshl_add_u64 v[56:57], v[52:53], 2, s[28:29]
	v_ashrrev_i32_e32 v51, 31, v50
	v_lshl_add_u64 v[52:53], v[52:53], 1, s[30:31]
	v_lshl_add_u64 v[54:55], v[50:51], 2, s[14:15]
	s_waitcnt vmcnt(0)
	v_pk_mul_f32 v[46:47], v[46:47], v[48:49] op_sel_hi:[1,0]
	v_pk_mul_f32 v[44:45], v[44:45], v[48:49] op_sel_hi:[1,0]
	v_pk_mul_f32 v[42:43], v[42:43], v[48:49] op_sel_hi:[1,0]
	v_pk_mul_f32 v[40:41], v[40:41], v[48:49] op_sel_hi:[1,0]
	v_pk_mul_f32 v[38:39], v[38:39], v[48:49] op_sel_hi:[1,0]
	v_pk_mul_f32 v[36:37], v[36:37], v[48:49] op_sel_hi:[1,0]
	v_pk_mul_f32 v[34:35], v[34:35], v[48:49] op_sel_hi:[1,0]
	v_pk_mul_f32 v[32:33], v[32:33], v[48:49] op_sel_hi:[1,0]
	global_store_dwordx4 v[56:57], v[44:47], off nt
	global_store_dwordx4 v[56:57], v[40:43], off offset:16 nt
	s_nop 0
	v_cvt_pk_bf16_f32 v44, v44, v45
	v_cvt_pk_bf16_f32 v45, v46, v47
	v_cvt_pk_bf16_f32 v46, v40, v41
	v_cvt_pk_bf16_f32 v47, v42, v43
	v_cvt_pk_bf16_f32 v40, v36, v37
	v_cvt_pk_bf16_f32 v41, v38, v39
	v_cvt_pk_bf16_f32 v42, v32, v33
	v_cvt_pk_bf16_f32 v43, v34, v35
	global_store_dwordx4 v[52:53], v[44:47], off
	global_store_dwordx4 v[56:57], v[36:39], off offset:512 nt
	global_store_dwordx4 v[56:57], v[32:35], off offset:528 nt
	global_store_dwordx4 v[52:53], v[40:43], off offset:256
	global_load_dword v32, v[54:55], off
	v_lshlrev_b64 v[36:37], 10, v[50:51]
	v_lshl_add_u64 v[36:37], v[36:37], 0, v[144:145]
	v_add_u32_e32 v34, 0xb0, v146
	v_lshl_add_u64 v[40:41], v[36:37], 2, s[28:29]
	v_ashrrev_i32_e32 v35, 31, v34
	v_lshl_add_u64 v[36:37], v[36:37], 1, s[30:31]
	v_lshl_add_u64 v[38:39], v[34:35], 2, s[14:15]
	s_waitcnt vmcnt(0)
	v_pk_mul_f32 v[30:31], v[30:31], v[32:33] op_sel_hi:[1,0]
	v_pk_mul_f32 v[28:29], v[28:29], v[32:33] op_sel_hi:[1,0]
	v_pk_mul_f32 v[26:27], v[26:27], v[32:33] op_sel_hi:[1,0]
	v_pk_mul_f32 v[24:25], v[24:25], v[32:33] op_sel_hi:[1,0]
	v_pk_mul_f32 v[22:23], v[22:23], v[32:33] op_sel_hi:[1,0]
	v_pk_mul_f32 v[20:21], v[20:21], v[32:33] op_sel_hi:[1,0]
	v_pk_mul_f32 v[18:19], v[18:19], v[32:33] op_sel_hi:[1,0]
	v_pk_mul_f32 v[16:17], v[16:17], v[32:33] op_sel_hi:[1,0]
	global_store_dwordx4 v[40:41], v[28:31], off nt
	global_store_dwordx4 v[40:41], v[24:27], off offset:16 nt
	s_nop 0
	v_cvt_pk_bf16_f32 v28, v28, v29
	v_cvt_pk_bf16_f32 v29, v30, v31
	v_cvt_pk_bf16_f32 v30, v24, v25
	v_cvt_pk_bf16_f32 v31, v26, v27
	v_cvt_pk_bf16_f32 v24, v20, v21
	v_cvt_pk_bf16_f32 v25, v22, v23
	v_cvt_pk_bf16_f32 v26, v16, v17
	v_cvt_pk_bf16_f32 v27, v18, v19
	global_store_dwordx4 v[36:37], v[28:31], off
	global_store_dwordx4 v[40:41], v[20:23], off offset:512 nt
	global_store_dwordx4 v[40:41], v[16:19], off offset:528 nt
	global_store_dwordx4 v[36:37], v[24:27], off offset:256
	global_load_dword v16, v[38:39], off
	v_lshlrev_b64 v[18:19], 10, v[34:35]
	v_lshl_add_u64 v[18:19], v[18:19], 0, v[144:145]
	v_lshl_add_u64 v[20:21], v[18:19], 2, s[28:29]
	v_lshl_add_u64 v[18:19], v[18:19], 1, s[30:31]
	s_waitcnt vmcnt(0)
	v_pk_mul_f32 v[14:15], v[14:15], v[16:17] op_sel_hi:[1,0]
	v_pk_mul_f32 v[12:13], v[12:13], v[16:17] op_sel_hi:[1,0]
	v_pk_mul_f32 v[10:11], v[10:11], v[16:17] op_sel_hi:[1,0]
	v_pk_mul_f32 v[8:9], v[8:9], v[16:17] op_sel_hi:[1,0]
	v_pk_mul_f32 v[6:7], v[6:7], v[16:17] op_sel_hi:[1,0]
	v_pk_mul_f32 v[4:5], v[4:5], v[16:17] op_sel_hi:[1,0]
	v_pk_mul_f32 v[2:3], v[2:3], v[16:17] op_sel_hi:[1,0]
	v_pk_mul_f32 v[0:1], v[0:1], v[16:17] op_sel_hi:[1,0]
	global_store_dwordx4 v[20:21], v[12:15], off nt
	global_store_dwordx4 v[20:21], v[8:11], off offset:16 nt
	s_nop 0
	v_cvt_pk_bf16_f32 v12, v12, v13
	v_cvt_pk_bf16_f32 v13, v14, v15
	v_cvt_pk_bf16_f32 v14, v8, v9
	v_cvt_pk_bf16_f32 v15, v10, v11
	v_cvt_pk_bf16_f32 v8, v4, v5
	v_cvt_pk_bf16_f32 v9, v6, v7
	v_cvt_pk_bf16_f32 v10, v0, v1
	v_cvt_pk_bf16_f32 v11, v2, v3
	global_store_dwordx4 v[18:19], v[12:15], off
	global_store_dwordx4 v[20:21], v[4:7], off offset:512 nt
	global_store_dwordx4 v[20:21], v[0:3], off offset:528 nt
	global_store_dwordx4 v[18:19], v[8:11], off offset:256
	s_cbranch_vccnz .LBB0_382
	s_andn2_b64 vcc, exec, s[12:13]
	s_cbranch_vccnz .LBB0_381
	s_barrier
	s_branch .LBB0_381

; __device__ __forceinline__ float dot4(f32x4 a, f32x4 b) { return (a[0] * b[0] + a[1] * b[1]) + (a[2] * b[2] + a[3] * b[3]); }
; __device__ __forceinline__ f32x4 unpack4(u32x2 w) { return (f32x4){bflo(w.x), bfhi(w.x), bflo(w.y), bfhi(w.y)}; }
; __device__ __forceinline__ void final_norm(Frame& F0) {
;     ...
;     for (int p = gwx; p < SEQ / 8; p += NGX) {
;         const int m0 = F.xq * SEQ + 8 * p;
;         u32x2 pk[8][4];
; #pragma unroll
;         for (int r = 0; r < 8; ++r) {
;             const u32x2* src = (const u32x2*)(((bf16_t*)(F.ws + WS_XB)) + (size_t)(m0 + r) * D) + lane;
; #pragma unroll
;             for (int jj = 0; jj < 4; ++jj) pk[r][jj] = src[64 * jj];
;         }
;         float s[8];
; #pragma unroll
;         for (int r = 0; r < 8; ++r) {
;             s[r] = 0.f;
; #pragma unroll
;             for (int jj = 0; jj < 4; ++jj) { const f32x4 t = unpack4(pk[r][jj]); s[r] += dot4(t, t); }
;         }
.LBB0_2365:
	s_add_i32 s12, s8, -7
	s_ashr_i32 s13, s12, 31
	s_lshl_b64 s[0:1], s[12:13], 11
	v_lshl_add_u64 v[40:41], v[34:35], 0, s[0:1]
	global_load_dwordx2 v[42:43], v[40:41], off
	global_load_dwordx2 v[44:45], v[40:41], off offset:512
	global_load_dwordx2 v[52:53], v[40:41], off offset:1024
	global_load_dwordx2 v[58:59], v[40:41], off offset:1536
	s_add_i32 s14, s8, -6
	s_ashr_i32 s15, s14, 31
	s_lshl_b64 s[0:1], s[14:15], 11
	v_lshl_add_u64 v[40:41], v[34:35], 0, s[0:1]
	global_load_dwordx2 v[60:61], v[40:41], off
	global_load_dwordx2 v[62:63], v[40:41], off offset:512
	global_load_dwordx2 v[70:71], v[40:41], off offset:1024
	global_load_dwordx2 v[82:83], v[40:41], off offset:1536
	s_add_i32 s16, s8, -5
	s_ashr_i32 s17, s16, 31
	s_lshl_b64 s[0:1], s[16:17], 11
	v_lshl_add_u64 v[40:41], v[34:35], 0, s[0:1]
	global_load_dwordx2 v[84:85], v[40:41], off
	global_load_dwordx2 v[80:81], v[40:41], off offset:512
	global_load_dwordx2 v[78:79], v[40:41], off offset:1024
	global_load_dwordx2 v[76:77], v[40:41], off offset:1536
	s_add_i32 s18, s8, -4
	s_ashr_i32 s19, s18, 31
	s_lshl_b64 s[0:1], s[18:19], 11
	v_lshl_add_u64 v[40:41], v[34:35], 0, s[0:1]
	global_load_dwordx2 v[100:101], v[40:41], off
	global_load_dwordx2 v[98:99], v[40:41], off offset:512
	global_load_dwordx2 v[96:97], v[40:41], off offset:1024
	global_load_dwordx2 v[94:95], v[40:41], off offset:1536
	s_add_i32 s20, s8, -3
	s_ashr_i32 s21, s20, 31
	s_lshl_b64 s[0:1], s[20:21], 11
	v_lshl_add_u64 v[40:41], v[34:35], 0, s[0:1]
	global_load_dwordx2 v[118:119], v[40:41], off
	global_load_dwordx2 v[116:117], v[40:41], off offset:512
	global_load_dwordx2 v[114:115], v[40:41], off offset:1024
	global_load_dwordx2 v[112:113], v[40:41], off offset:1536
	s_add_i32 s22, s8, -2
	s_ashr_i32 s23, s22, 31
	s_lshl_b64 s[0:1], s[22:23], 11
	v_lshl_add_u64 v[40:41], v[34:35], 0, s[0:1]
	global_load_dwordx2 v[136:137], v[40:41], off
	global_load_dwordx2 v[134:135], v[40:41], off offset:512
	global_load_dwordx2 v[132:133], v[40:41], off offset:1024
	global_load_dwordx2 v[130:131], v[40:41], off offset:1536
	s_add_i32 s24, s8, -1
	s_ashr_i32 s25, s24, 31
	s_lshl_b64 s[0:1], s[24:25], 11
	v_lshl_add_u64 v[40:41], v[34:35], 0, s[0:1]
	global_load_dwordx2 v[154:155], v[40:41], off
	global_load_dwordx2 v[152:153], v[40:41], off offset:512
	global_load_dwordx2 v[150:151], v[40:41], off offset:1024
	global_load_dwordx2 v[148:149], v[40:41], off offset:1536
	s_ashr_i32 s9, s8, 31
	s_lshl_b64 s[0:1], s[8:9], 11
	v_lshl_add_u64 v[40:41], v[34:35], 0, s[0:1]
	global_load_dwordx2 v[172:173], v[40:41], off
	global_load_dwordx2 v[170:171], v[40:41], off offset:512
	global_load_dwordx2 v[168:169], v[40:41], off offset:1024
	global_load_dwordx2 v[166:167], v[40:41], off offset:1536
	v_add_u32_e32 v196, v196, v189
	s_waitcnt vmcnt(31)
	v_and_b32_e32 v57, 0xffff0000, v43
	v_and_b32_e32 v55, 0xffff0000, v42
	v_lshlrev_b32_e32 v56, 16, v43
	v_mul_f32_e32 v40, v57, v57
	s_waitcnt vmcnt(30)
	v_and_b32_e32 v49, 0xffff0000, v45
	v_and_b32_e32 v48, 0xffff0000, v44
	v_lshlrev_b32_e32 v54, 16, v42
	v_pk_fma_f32 v[64:65], v[56:57], v[56:57], v[40:41] op_sel_hi:[1,1,0]
	v_lshlrev_b32_e32 v47, 16, v45
	v_lshlrev_b32_e32 v46, 16, v44
	v_pk_mul_f32 v[40:41], v[48:49], v[48:49]
	s_waitcnt vmcnt(28)
	v_and_b32_e32 v43, 0xffff0000, v58
	v_mul_f32_e32 v42, v55, v55
	v_pk_fma_f32 v[66:67], v[46:47], v[46:47], v[40:41]
	v_lshlrev_b32_e32 v45, 16, v58
	v_lshlrev_b32_e32 v40, 16, v59
	v_and_b32_e32 v41, 0xffff0000, v59
	v_pk_fma_f32 v[58:59], v[54:55], v[54:55], v[42:43] op_sel_hi:[1,1,0]
	v_mov_b32_e32 v68, v64
	v_mov_b32_e32 v44, v58
	v_mov_b32_e32 v69, v45
	v_pk_add_f32 v[58:59], v[58:59], v[64:65]
	v_pk_mul_f32 v[64:65], v[44:45], v[68:69]
	v_and_b32_e32 v51, 0xffff0000, v52
	v_mul_f32_e32 v72, v43, v43
	v_mov_b32_e32 v59, v65
	v_pk_add_f32 v[64:65], v[66:67], v[66:67] op_sel:[0,1] op_sel_hi:[1,0]
	v_lshlrev_b32_e32 v50, 16, v52
	v_lshlrev_b32_e32 v52, 16, v53
	v_and_b32_e32 v53, 0xffff0000, v53
	v_mov_b32_e32 v65, v72
	v_mul_f32_e32 v42, v51, v51
	v_pk_add_f32 v[58:59], v[58:59], v[64:65]
	v_pk_fma_f32 v[64:65], v[50:51], v[50:51], v[42:43] op_sel_hi:[1,1,0]
	v_mul_f32_e32 v42, v53, v53
	v_mul_f32_e32 v73, v40, v40
	v_mul_f32_e32 v74, v41, v41
	v_pk_fma_f32 v[66:67], v[52:53], v[52:53], v[42:43] op_sel_hi:[1,1,0]
	v_mov_b32_e32 v65, v73
	v_mov_b32_e32 v67, v74
	s_waitcnt vmcnt(27)
	v_and_b32_e32 v75, 0xffff0000, v61
	v_pk_add_f32 v[64:65], v[64:65], v[66:67]
	v_and_b32_e32 v73, 0xffff0000, v60
	v_lshlrev_b32_e32 v74, 16, v61
	v_mul_f32_e32 v42, v75, v75
	s_waitcnt vmcnt(26)
	v_and_b32_e32 v67, 0xffff0000, v63
	v_and_b32_e32 v66, 0xffff0000, v62
	v_pk_add_f32 v[184:185], v[58:59], v[64:65]
	v_lshlrev_b32_e32 v72, 16, v60
	v_pk_fma_f32 v[86:87], v[74:75], v[74:75], v[42:43] op_sel_hi:[1,1,0]
	v_lshlrev_b32_e32 v65, 16, v63
	v_lshlrev_b32_e32 v64, 16, v62
	v_pk_mul_f32 v[58:59], v[66:67], v[66:67]
	v_mul_f32_e32 v42, v73, v73
	v_pk_fma_f32 v[88:89], v[64:65], v[64:65], v[58:59]
	s_waitcnt vmcnt(24)
	v_lshlrev_b32_e32 v63, 16, v82
	v_and_b32_e32 v61, 0xffff0000, v82
	v_lshlrev_b32_e32 v58, 16, v83
	v_and_b32_e32 v59, 0xffff0000, v83
	v_pk_fma_f32 v[82:83], v[72:73], v[72:73], v[42:43] op_sel_hi:[1,1,0]
	v_mov_b32_e32 v90, v86
	v_mov_b32_e32 v62, v82
	v_mov_b32_e32 v91, v63
	v_pk_add_f32 v[82:83], v[82:83], v[86:87]
	v_pk_mul_f32 v[86:87], v[62:63], v[90:91]
	v_and_b32_e32 v69, 0xffff0000, v70
	v_mul_f32_e32 v44, v61, v61
	v_mov_b32_e32 v83, v87
	v_pk_add_f32 v[86:87], v[88:89], v[88:89] op_sel:[0,1] op_sel_hi:[1,0]
	v_lshlrev_b32_e32 v68, 16, v70
	v_lshlrev_b32_e32 v70, 16, v71
	v_and_b32_e32 v71, 0xffff0000, v71
	v_mov_b32_e32 v87, v44
	v_mul_f32_e32 v42, v69, v69
	v_pk_add_f32 v[82:83], v[82:83], v[86:87]
	v_pk_fma_f32 v[86:87], v[68:69], v[68:69], v[42:43] op_sel_hi:[1,1,0]
	v_mul_f32_e32 v42, v71, v71
	v_mul_f32_e32 v60, v58, v58
	v_mul_f32_e32 v92, v59, v59
	v_pk_fma_f32 v[88:89], v[70:71], v[70:71], v[42:43] op_sel_hi:[1,1,0]
	v_mov_b32_e32 v87, v60
	v_mov_b32_e32 v89, v92
	s_waitcnt vmcnt(23)
; __device__ __forceinline__ float dot4(f32x4 a, f32x4 b) { return (a[0] * b[0] + a[1] * b[1]) + (a[2] * b[2] + a[3] * b[3]); }
; __device__ __forceinline__ f32x4 unpack4(u32x2 w) { return (f32x4){bflo(w.x), bfhi(w.x), bflo(w.y), bfhi(w.y)}; }
; __device__ __forceinline__ void final_norm(Frame& F0) {
;     ...
;         float s[8];
; #pragma unroll
;         for (int r = 0; r < 8; ++r) {
;             s[r] = 0.f;
; #pragma unroll
;             for (int jj = 0; jj < 4; ++jj) { const f32x4 t = unpack4(pk[r][jj]); s[r] += dot4(t, t); }
;         }
	v_and_b32_e32 v93, 0xffff0000, v85
	v_pk_add_f32 v[86:87], v[86:87], v[88:89]
	v_lshlrev_b32_e32 v90, 16, v84
	v_and_b32_e32 v91, 0xffff0000, v84
	v_lshlrev_b32_e32 v92, 16, v85
	v_mul_f32_e32 v42, v93, v93
	s_waitcnt vmcnt(22)
	v_and_b32_e32 v85, 0xffff0000, v81
	v_and_b32_e32 v84, 0xffff0000, v80
	v_pk_add_f32 v[186:187], v[82:83], v[86:87]
	v_pk_fma_f32 v[102:103], v[92:93], v[92:93], v[42:43] op_sel_hi:[1,1,0]
	v_lshlrev_b32_e32 v83, 16, v81
	v_lshlrev_b32_e32 v82, 16, v80
	v_pk_mul_f32 v[80:81], v[84:85], v[84:85]
	v_mul_f32_e32 v42, v91, v91
	v_pk_fma_f32 v[104:105], v[82:83], v[82:83], v[80:81]
	s_waitcnt vmcnt(20)
	v_lshlrev_b32_e32 v81, 16, v76
	v_pk_fma_f32 v[106:107], v[90:91], v[90:91], v[42:43] op_sel_hi:[1,1,0]
	v_lshlrev_b32_e32 v88, 16, v79
	v_and_b32_e32 v89, 0xffff0000, v79
	v_and_b32_e32 v79, 0xffff0000, v76
	v_mov_b32_e32 v80, v106
	v_mov_b32_e32 v108, v102
	v_mov_b32_e32 v109, v81
	v_and_b32_e32 v87, 0xffff0000, v78
	v_mul_f32_e32 v44, v79, v79
	v_pk_add_f32 v[102:103], v[106:107], v[102:103]
	v_pk_mul_f32 v[106:107], v[80:81], v[108:109]
	v_pk_add_f32 v[104:105], v[104:105], v[104:105] op_sel:[0,1] op_sel_hi:[1,0]
	v_lshlrev_b32_e32 v86, 16, v78
	v_mov_b32_e32 v103, v107
	v_mov_b32_e32 v105, v44
	v_mul_f32_e32 v42, v87, v87
	v_lshlrev_b32_e32 v76, 16, v77
	v_and_b32_e32 v77, 0xffff0000, v77
	v_pk_add_f32 v[102:103], v[102:103], v[104:105]
	v_pk_fma_f32 v[104:105], v[86:87], v[86:87], v[42:43] op_sel_hi:[1,1,0]
	v_mul_f32_e32 v42, v89, v89
	v_mul_f32_e32 v60, v76, v76
	v_mul_f32_e32 v62, v77, v77
	v_pk_fma_f32 v[106:107], v[88:89], v[88:89], v[42:43] op_sel_hi:[1,1,0]
	v_mov_b32_e32 v105, v60
	v_mov_b32_e32 v107, v62
	v_pk_add_f32 v[104:105], v[104:105], v[106:107]
	s_waitcnt vmcnt(19)
	v_and_b32_e32 v111, 0xffff0000, v101
	v_pk_add_f32 v[198:199], v[102:103], v[104:105]
	v_and_b32_e32 v109, 0xffff0000, v100
	v_lshlrev_b32_e32 v110, 16, v101
	v_mul_f32_e32 v42, v111, v111
	s_waitcnt vmcnt(18)
	v_and_b32_e32 v103, 0xffff0000, v99
	v_and_b32_e32 v102, 0xffff0000, v98
	v_lshlrev_b32_e32 v108, 16, v100
	v_pk_fma_f32 v[120:121], v[110:111], v[110:111], v[42:43] op_sel_hi:[1,1,0]
	v_lshlrev_b32_e32 v101, 16, v99
	v_lshlrev_b32_e32 v100, 16, v98
	v_pk_mul_f32 v[98:99], v[102:103], v[102:103]
	v_mul_f32_e32 v42, v109, v109
	v_pk_fma_f32 v[122:123], v[100:101], v[100:101], v[98:99]
	s_waitcnt vmcnt(16)
	v_lshlrev_b32_e32 v99, 16, v94
	v_pk_fma_f32 v[124:125], v[108:109], v[108:109], v[42:43] op_sel_hi:[1,1,0]
	v_lshlrev_b32_e32 v106, 16, v97
	v_and_b32_e32 v107, 0xffff0000, v97
	v_and_b32_e32 v97, 0xffff0000, v94
	v_mov_b32_e32 v98, v124
	v_mov_b32_e32 v126, v120
	v_mov_b32_e32 v127, v99
	v_and_b32_e32 v105, 0xffff0000, v96
	v_mul_f32_e32 v44, v97, v97
	v_pk_add_f32 v[120:121], v[124:125], v[120:121]
	v_pk_mul_f32 v[124:125], v[98:99], v[126:127]
	v_pk_add_f32 v[122:123], v[122:123], v[122:123] op_sel:[0,1] op_sel_hi:[1,0]
	v_lshlrev_b32_e32 v104, 16, v96
	v_mov_b32_e32 v121, v125
	v_mov_b32_e32 v123, v44
	v_mul_f32_e32 v42, v105, v105
	v_lshlrev_b32_e32 v94, 16, v95
	v_and_b32_e32 v95, 0xffff0000, v95
	v_pk_add_f32 v[120:121], v[120:121], v[122:123]
	v_pk_fma_f32 v[122:123], v[104:105], v[104:105], v[42:43] op_sel_hi:[1,1,0]
	v_mul_f32_e32 v42, v107, v107
	v_mul_f32_e32 v60, v94, v94
	v_mul_f32_e32 v62, v95, v95
	v_pk_fma_f32 v[124:125], v[106:107], v[106:107], v[42:43] op_sel_hi:[1,1,0]
	v_mov_b32_e32 v123, v60
	v_mov_b32_e32 v125, v62
	v_pk_add_f32 v[122:123], v[122:123], v[124:125]
	s_waitcnt vmcnt(15)
	v_and_b32_e32 v129, 0xffff0000, v119
	v_pk_add_f32 v[200:201], v[120:121], v[122:123]
	v_and_b32_e32 v127, 0xffff0000, v118
	v_lshlrev_b32_e32 v128, 16, v119
	v_mul_f32_e32 v42, v129, v129
	s_waitcnt vmcnt(14)
	v_and_b32_e32 v121, 0xffff0000, v117
	v_and_b32_e32 v120, 0xffff0000, v116
	v_lshlrev_b32_e32 v126, 16, v118
	v_pk_fma_f32 v[138:139], v[128:129], v[128:129], v[42:43] op_sel_hi:[1,1,0]
	v_lshlrev_b32_e32 v119, 16, v117
	v_lshlrev_b32_e32 v118, 16, v116
	v_pk_mul_f32 v[116:117], v[120:121], v[120:121]
	v_mul_f32_e32 v42, v127, v127
	v_pk_fma_f32 v[140:141], v[118:119], v[118:119], v[116:117]
	s_waitcnt vmcnt(12)
	v_lshlrev_b32_e32 v117, 16, v112
	v_pk_fma_f32 v[142:143], v[126:127], v[126:127], v[42:43] op_sel_hi:[1,1,0]
	v_lshlrev_b32_e32 v124, 16, v115
	v_and_b32_e32 v125, 0xffff0000, v115
	v_and_b32_e32 v115, 0xffff0000, v112
	v_mov_b32_e32 v116, v142
	v_mov_b32_e32 v144, v138
	v_mov_b32_e32 v145, v117
	v_and_b32_e32 v123, 0xffff0000, v114
	v_mul_f32_e32 v44, v115, v115
	v_pk_add_f32 v[138:139], v[142:143], v[138:139]
	v_pk_mul_f32 v[142:143], v[116:117], v[144:145]
	v_pk_add_f32 v[140:141], v[140:141], v[140:141] op_sel:[0,1] op_sel_hi:[1,0]
	v_lshlrev_b32_e32 v122, 16, v114
	v_mov_b32_e32 v139, v143
	v_mov_b32_e32 v141, v44
	v_mul_f32_e32 v42, v123, v123
	v_lshlrev_b32_e32 v112, 16, v113
	v_and_b32_e32 v113, 0xffff0000, v113
	v_pk_add_f32 v[138:139], v[138:139], v[140:141]
	v_pk_fma_f32 v[140:141], v[122:123], v[122:123], v[42:43] op_sel_hi:[1,1,0]
	v_mul_f32_e32 v42, v125, v125
	v_mul_f32_e32 v60, v112, v112
	v_mul_f32_e32 v62, v113, v113
	v_pk_fma_f32 v[142:143], v[124:125], v[124:125], v[42:43] op_sel_hi:[1,1,0]
	v_mov_b32_e32 v141, v60
	v_mov_b32_e32 v143, v62
	v_pk_add_f32 v[140:141], v[140:141], v[142:143]
	s_waitcnt vmcnt(11)
	v_and_b32_e32 v147, 0xffff0000, v137
	v_pk_add_f32 v[202:203], v[138:139], v[140:141]
	v_and_b32_e32 v145, 0xffff0000, v136
	v_lshlrev_b32_e32 v146, 16, v137
	v_mul_f32_e32 v42, v147, v147
	s_waitcnt vmcnt(10)
; __device__ __forceinline__ float dot4(f32x4 a, f32x4 b) { return (a[0] * b[0] + a[1] * b[1]) + (a[2] * b[2] + a[3] * b[3]); }
; __device__ __forceinline__ f32x4 unpack4(u32x2 w) { return (f32x4){bflo(w.x), bfhi(w.x), bflo(w.y), bfhi(w.y)}; }
; __device__ __forceinline__ void final_norm(Frame& F0) {
;     ...
;         float s[8];
; #pragma unroll
;         for (int r = 0; r < 8; ++r) {
;             s[r] = 0.f;
; #pragma unroll
;             for (int jj = 0; jj < 4; ++jj) { const f32x4 t = unpack4(pk[r][jj]); s[r] += dot4(t, t); }
;         }
; #pragma unroll
;         for (int r = 0; r < 8; ++r) s[r] = rsqrtf(wave_sum(s[r], lane) * (1.0f / D) + EPS);
	v_and_b32_e32 v139, 0xffff0000, v135
	v_and_b32_e32 v138, 0xffff0000, v134
	v_lshlrev_b32_e32 v144, 16, v136
	v_pk_fma_f32 v[156:157], v[146:147], v[146:147], v[42:43] op_sel_hi:[1,1,0]
	v_lshlrev_b32_e32 v137, 16, v135
	v_lshlrev_b32_e32 v136, 16, v134
	v_pk_mul_f32 v[134:135], v[138:139], v[138:139]
	v_mul_f32_e32 v42, v145, v145
	v_pk_fma_f32 v[158:159], v[136:137], v[136:137], v[134:135]
	s_waitcnt vmcnt(8)
	v_lshlrev_b32_e32 v135, 16, v130
	v_pk_fma_f32 v[160:161], v[144:145], v[144:145], v[42:43] op_sel_hi:[1,1,0]
	v_lshlrev_b32_e32 v142, 16, v133
	v_and_b32_e32 v143, 0xffff0000, v133
	v_and_b32_e32 v133, 0xffff0000, v130
	v_mov_b32_e32 v134, v160
	v_mov_b32_e32 v162, v156
	v_mov_b32_e32 v163, v135
	v_and_b32_e32 v141, 0xffff0000, v132
	v_mul_f32_e32 v44, v133, v133
	v_pk_add_f32 v[156:157], v[160:161], v[156:157]
	v_pk_mul_f32 v[160:161], v[134:135], v[162:163]
	v_pk_add_f32 v[158:159], v[158:159], v[158:159] op_sel:[0,1] op_sel_hi:[1,0]
	v_lshlrev_b32_e32 v140, 16, v132
	v_mov_b32_e32 v157, v161
	v_mov_b32_e32 v159, v44
	v_mul_f32_e32 v42, v141, v141
	v_lshlrev_b32_e32 v130, 16, v131
	v_and_b32_e32 v131, 0xffff0000, v131
	v_pk_add_f32 v[156:157], v[156:157], v[158:159]
	v_pk_fma_f32 v[158:159], v[140:141], v[140:141], v[42:43] op_sel_hi:[1,1,0]
	v_mul_f32_e32 v42, v143, v143
	v_mul_f32_e32 v60, v130, v130
	v_mul_f32_e32 v62, v131, v131
	v_pk_fma_f32 v[160:161], v[142:143], v[142:143], v[42:43] op_sel_hi:[1,1,0]
	v_mov_b32_e32 v159, v60
	v_mov_b32_e32 v161, v62
	v_pk_add_f32 v[158:159], v[158:159], v[160:161]
	s_waitcnt vmcnt(7)
	v_and_b32_e32 v165, 0xffff0000, v155
	v_pk_add_f32 v[204:205], v[156:157], v[158:159]
	v_and_b32_e32 v163, 0xffff0000, v154
	v_lshlrev_b32_e32 v164, 16, v155
	v_mul_f32_e32 v42, v165, v165
	s_waitcnt vmcnt(6)
	v_and_b32_e32 v157, 0xffff0000, v153
	v_and_b32_e32 v156, 0xffff0000, v152
	v_lshlrev_b32_e32 v162, 16, v154
	v_pk_fma_f32 v[174:175], v[164:165], v[164:165], v[42:43] op_sel_hi:[1,1,0]
	v_lshlrev_b32_e32 v155, 16, v153
	v_lshlrev_b32_e32 v154, 16, v152
	v_pk_mul_f32 v[152:153], v[156:157], v[156:157]
	v_mul_f32_e32 v42, v163, v163
	v_pk_fma_f32 v[176:177], v[154:155], v[154:155], v[152:153]
	s_waitcnt vmcnt(4)
	v_lshlrev_b32_e32 v153, 16, v148
	v_pk_fma_f32 v[178:179], v[162:163], v[162:163], v[42:43] op_sel_hi:[1,1,0]
	v_lshlrev_b32_e32 v160, 16, v151
	v_and_b32_e32 v161, 0xffff0000, v151
	v_and_b32_e32 v151, 0xffff0000, v148
	v_mov_b32_e32 v152, v178
	v_mov_b32_e32 v180, v174
	v_mov_b32_e32 v181, v153
	v_and_b32_e32 v159, 0xffff0000, v150
	v_mul_f32_e32 v44, v151, v151
	v_pk_add_f32 v[174:175], v[178:179], v[174:175]
	v_pk_mul_f32 v[178:179], v[152:153], v[180:181]
	v_pk_add_f32 v[176:177], v[176:177], v[176:177] op_sel:[0,1] op_sel_hi:[1,0]
	v_lshlrev_b32_e32 v158, 16, v150
	v_mov_b32_e32 v175, v179
	v_mov_b32_e32 v177, v44
	v_mul_f32_e32 v42, v159, v159
	v_lshlrev_b32_e32 v148, 16, v149
	v_and_b32_e32 v149, 0xffff0000, v149
	v_pk_add_f32 v[174:175], v[174:175], v[176:177]
	v_pk_fma_f32 v[176:177], v[158:159], v[158:159], v[42:43] op_sel_hi:[1,1,0]
	v_mul_f32_e32 v42, v161, v161
	v_mul_f32_e32 v60, v148, v148
	v_mul_f32_e32 v62, v149, v149
	v_pk_fma_f32 v[178:179], v[160:161], v[160:161], v[42:43] op_sel_hi:[1,1,0]
	v_mov_b32_e32 v177, v60
	v_mov_b32_e32 v179, v62
	v_pk_add_f32 v[176:177], v[176:177], v[178:179]
	s_waitcnt vmcnt(3)
	v_and_b32_e32 v183, 0xffff0000, v173
	v_pk_add_f32 v[206:207], v[174:175], v[176:177]
	v_and_b32_e32 v181, 0xffff0000, v172
	v_lshlrev_b32_e32 v182, 16, v173
	v_mul_f32_e32 v42, v183, v183
	s_waitcnt vmcnt(2)
	v_and_b32_e32 v175, 0xffff0000, v171
	v_and_b32_e32 v174, 0xffff0000, v170
	v_lshlrev_b32_e32 v180, 16, v172
	v_pk_fma_f32 v[208:209], v[182:183], v[182:183], v[42:43] op_sel_hi:[1,1,0]
	v_lshlrev_b32_e32 v173, 16, v171
	v_lshlrev_b32_e32 v172, 16, v170
	v_pk_mul_f32 v[170:171], v[174:175], v[174:175]
	v_mul_f32_e32 v42, v181, v181
	v_pk_fma_f32 v[210:211], v[172:173], v[172:173], v[170:171]
	s_waitcnt vmcnt(0)
	v_lshlrev_b32_e32 v171, 16, v166
	v_pk_fma_f32 v[212:213], v[180:181], v[180:181], v[42:43] op_sel_hi:[1,1,0]
	v_lshlrev_b32_e32 v178, 16, v169
	v_and_b32_e32 v179, 0xffff0000, v169
	v_and_b32_e32 v169, 0xffff0000, v166
	v_mov_b32_e32 v170, v212
	v_mov_b32_e32 v214, v208
	v_mov_b32_e32 v215, v171
	v_and_b32_e32 v177, 0xffff0000, v168
	v_mul_f32_e32 v44, v169, v169
	v_pk_add_f32 v[208:209], v[212:213], v[208:209]
	v_pk_mul_f32 v[212:213], v[170:171], v[214:215]
	v_pk_add_f32 v[210:211], v[210:211], v[210:211] op_sel:[0,1] op_sel_hi:[1,0]
	v_lshlrev_b32_e32 v176, 16, v168
	v_mov_b32_e32 v209, v213
	v_mov_b32_e32 v211, v44
	v_mul_f32_e32 v42, v177, v177
	v_lshlrev_b32_e32 v166, 16, v167
	v_and_b32_e32 v167, 0xffff0000, v167
	v_pk_add_f32 v[208:209], v[208:209], v[210:211]
	v_pk_fma_f32 v[210:211], v[176:177], v[176:177], v[42:43] op_sel_hi:[1,1,0]
	v_mul_f32_e32 v42, v179, v179
	v_mul_f32_e32 v60, v166, v166
	v_mul_f32_e32 v62, v167, v167
	v_pk_fma_f32 v[212:213], v[178:179], v[178:179], v[42:43] op_sel_hi:[1,1,0]
	v_mov_b32_e32 v211, v60
	v_mov_b32_e32 v213, v62
	v_pk_add_f32 v[210:211], v[210:211], v[212:213]
	v_mov_b32_e32 v78, v81
	v_pk_add_f32 v[208:209], v[208:209], v[210:211]
	v_mov_b32_e32 v210, v186
	v_mov_b32_e32 v211, v184
	v_mov_b32_e32 v184, v187
	v_pk_add_f32 v[184:185], v[210:211], v[184:185]
	ds_bpermute_b32 v187, v190, v185
	ds_bpermute_b32 v186, v190, v184
	v_mov_b32_e32 v96, v99
	v_mov_b32_e32 v114, v117
	v_mov_b32_e32 v132, v135
	v_mov_b32_e32 v150, v153
	s_waitcnt lgkmcnt(0)
	v_pk_add_f32 v[184:185], v[184:185], v[186:187]
	ds_bpermute_b32 v187, v191, v185
	ds_bpermute_b32 v186, v191, v184
	v_mov_b32_e32 v168, v171
	s_waitcnt lgkmcnt(0)
; __device__ __forceinline__ f32x4 unpack4(u32x2 w) { return (f32x4){bflo(w.x), bfhi(w.x), bflo(w.y), bfhi(w.y)}; }
; __device__ __forceinline__ void final_norm(Frame& F0) {
;     ...
; #pragma unroll
;         for (int r = 0; r < 8; ++r) s[r] = rsqrtf(wave_sum(s[r], lane) * (1.0f / D) + EPS);
; #pragma unroll
;         for (int r = 0; r < 8; ++r) {
;             f32x4* dst = (f32x4*)(F.out + O_Y + (size_t)(m0 + r) * D) + lane;
; #pragma unroll
;             for (int jj = 0; jj < 4; ++jj) dst[64 * jj] = unpack4(pk[r][jj]) * s[r] * g[jj];
	v_pk_add_f32 v[184:185], v[184:185], v[186:187]
	ds_bpermute_b32 v187, v192, v185
	ds_bpermute_b32 v186, v192, v184
	s_waitcnt lgkmcnt(0)
	v_pk_add_f32 v[184:185], v[184:185], v[186:187]
	ds_bpermute_b32 v187, v193, v185
	ds_bpermute_b32 v186, v193, v184
	s_waitcnt lgkmcnt(0)
	v_pk_add_f32 v[184:185], v[184:185], v[186:187]
	ds_bpermute_b32 v187, v194, v185
	ds_bpermute_b32 v186, v194, v184
	s_waitcnt lgkmcnt(0)
	v_pk_add_f32 v[184:185], v[184:185], v[186:187]
	ds_bpermute_b32 v187, v195, v185
	ds_bpermute_b32 v186, v195, v184
	s_waitcnt lgkmcnt(0)
	v_pk_add_f32 v[184:185], v[184:185], v[186:187]
	s_nop 0
	v_pk_fma_f32 v[184:185], v[184:185], s[10:11], v[38:39] op_sel_hi:[1,0,0]
	s_nop 0
	v_mul_f32_e32 v42, 0x4b800000, v185
	v_cmp_gt_f32_e64 s[0:1], s29, v185
	v_cmp_gt_f32_e32 vcc, s29, v184
	s_nop 0
	v_cndmask_b32_e64 v42, v185, v42, s[0:1]
	v_rsq_f32_e32 v42, v42
	v_mov_b32_e32 v185, v198
	v_mov_b32_e32 v198, v201
	v_mul_f32_e32 v44, 0x45800000, v42
	v_cndmask_b32_e64 v44, v42, v44, s[0:1]
	v_mul_f32_e32 v42, 0x4b800000, v184
	v_cndmask_b32_e32 v42, v184, v42, vcc
	v_mov_b32_e32 v184, v200
	v_pk_add_f32 v[184:185], v[184:185], v[198:199]
	ds_bpermute_b32 v187, v190, v185
	ds_bpermute_b32 v186, v190, v184
	v_rsq_f32_e32 v42, v42
	v_pk_mul_f32 v[54:55], v[44:45], v[54:55] op_sel_hi:[0,1]
	v_pk_mul_f32 v[56:57], v[44:45], v[56:57] op_sel_hi:[0,1]
	v_pk_mul_f32 v[56:57], v[14:15], v[56:57]
	s_waitcnt lgkmcnt(0)
	v_pk_add_f32 v[184:185], v[184:185], v[186:187]
	ds_bpermute_b32 v187, v191, v185
	ds_bpermute_b32 v186, v191, v184
	v_mul_f32_e32 v60, 0x45800000, v42
	v_cndmask_b32_e32 v62, v42, v60, vcc
	v_pk_mul_f32 v[54:55], v[12:13], v[54:55]
	v_pk_mul_f32 v[40:41], v[44:45], v[40:41] op_sel_hi:[0,1]
	s_waitcnt lgkmcnt(0)
	v_pk_add_f32 v[184:185], v[184:185], v[186:187]
	ds_bpermute_b32 v187, v192, v185
	ds_bpermute_b32 v186, v192, v184
	s_waitcnt lgkmcnt(0)
	v_pk_add_f32 v[184:185], v[184:185], v[186:187]
	ds_bpermute_b32 v187, v193, v185
	ds_bpermute_b32 v186, v193, v184
	s_waitcnt lgkmcnt(0)
	v_pk_add_f32 v[184:185], v[184:185], v[186:187]
	ds_bpermute_b32 v187, v194, v185
	ds_bpermute_b32 v186, v194, v184
	s_waitcnt lgkmcnt(0)
	v_pk_add_f32 v[184:185], v[184:185], v[186:187]
	ds_bpermute_b32 v187, v195, v185
	ds_bpermute_b32 v186, v195, v184
	s_waitcnt lgkmcnt(0)
	v_pk_add_f32 v[184:185], v[184:185], v[186:187]
	s_nop 0
	v_pk_fma_f32 v[184:185], v[184:185], s[10:11], v[38:39] op_sel_hi:[1,0,0]
	s_nop 0
	v_mul_f32_e32 v42, 0x4b800000, v185
	v_cmp_gt_f32_e64 s[0:1], s29, v185
	v_cmp_gt_f32_e32 vcc, s29, v184
	s_nop 0
	v_cndmask_b32_e64 v42, v185, v42, s[0:1]
	v_rsq_f32_e32 v42, v42
	v_mov_b32_e32 v185, v202
	v_mov_b32_e32 v202, v205
	v_mul_f32_e32 v60, 0x45800000, v42
	v_cndmask_b32_e64 v80, v42, v60, s[0:1]
	v_mul_f32_e32 v42, 0x4b800000, v184
	v_cndmask_b32_e32 v42, v184, v42, vcc
	v_mov_b32_e32 v184, v204
	v_pk_add_f32 v[184:185], v[184:185], v[202:203]
	ds_bpermute_b32 v187, v190, v185
	ds_bpermute_b32 v186, v190, v184
	v_rsq_f32_e32 v42, v42
	s_waitcnt lgkmcnt(0)
	v_pk_add_f32 v[184:185], v[184:185], v[186:187]
	ds_bpermute_b32 v187, v191, v185
	ds_bpermute_b32 v186, v191, v184
	v_mul_f32_e32 v60, 0x45800000, v42
	v_cndmask_b32_e32 v98, v42, v60, vcc
	s_waitcnt lgkmcnt(0)
	v_pk_add_f32 v[184:185], v[184:185], v[186:187]
	ds_bpermute_b32 v187, v192, v185
	ds_bpermute_b32 v186, v192, v184
	s_waitcnt lgkmcnt(0)
	v_pk_add_f32 v[184:185], v[184:185], v[186:187]
	ds_bpermute_b32 v187, v193, v185
	ds_bpermute_b32 v186, v193, v184
	s_waitcnt lgkmcnt(0)
	v_pk_add_f32 v[184:185], v[184:185], v[186:187]
	ds_bpermute_b32 v187, v194, v185
	ds_bpermute_b32 v186, v194, v184
	s_waitcnt lgkmcnt(0)
	v_pk_add_f32 v[184:185], v[184:185], v[186:187]
	ds_bpermute_b32 v187, v195, v185
	ds_bpermute_b32 v186, v195, v184
	s_waitcnt lgkmcnt(0)
	v_pk_add_f32 v[184:185], v[184:185], v[186:187]
	s_nop 0
	v_pk_fma_f32 v[184:185], v[184:185], s[10:11], v[38:39] op_sel_hi:[1,0,0]
	s_nop 0
	v_mul_f32_e32 v42, 0x4b800000, v185
	v_cmp_gt_f32_e64 s[0:1], s29, v185
	v_cmp_gt_f32_e32 vcc, s29, v184
	s_nop 0
	v_cndmask_b32_e64 v42, v185, v42, s[0:1]
	v_rsq_f32_e32 v42, v42
	v_mov_b32_e32 v185, v206
	v_mov_b32_e32 v206, v209
	v_mul_f32_e32 v60, 0x45800000, v42
	v_cndmask_b32_e64 v116, v42, v60, s[0:1]
	v_mul_f32_e32 v42, 0x4b800000, v184
	v_cndmask_b32_e32 v42, v184, v42, vcc
	v_mov_b32_e32 v184, v208
	v_pk_add_f32 v[184:185], v[184:185], v[206:207]
	ds_bpermute_b32 v187, v190, v185
	ds_bpermute_b32 v186, v190, v184
	v_rsq_f32_e32 v42, v42
	s_waitcnt lgkmcnt(0)
	v_pk_add_f32 v[184:185], v[184:185], v[186:187]
	ds_bpermute_b32 v187, v191, v185
	ds_bpermute_b32 v186, v191, v184
	v_mul_f32_e32 v60, 0x45800000, v42
	v_cndmask_b32_e32 v134, v42, v60, vcc
	s_waitcnt lgkmcnt(0)
	v_pk_add_f32 v[184:185], v[184:185], v[186:187]
	ds_bpermute_b32 v187, v192, v185
	ds_bpermute_b32 v186, v192, v184
	s_waitcnt lgkmcnt(0)
	v_pk_add_f32 v[184:185], v[184:185], v[186:187]
	ds_bpermute_b32 v187, v193, v185
	ds_bpermute_b32 v186, v193, v184
	s_waitcnt lgkmcnt(0)
	v_pk_add_f32 v[184:185], v[184:185], v[186:187]
	ds_bpermute_b32 v187, v194, v185
	ds_bpermute_b32 v186, v194, v184
	s_waitcnt lgkmcnt(0)
	v_pk_add_f32 v[184:185], v[184:185], v[186:187]
	ds_bpermute_b32 v187, v195, v185
	ds_bpermute_b32 v186, v195, v184
	s_waitcnt lgkmcnt(0)
; __device__ __forceinline__ f32x4 unpack4(u32x2 w) { return (f32x4){bflo(w.x), bfhi(w.x), bflo(w.y), bfhi(w.y)}; }
; __device__ __forceinline__ void final_norm(Frame& F0) {
;     ...
;         for (int r = 0; r < 8; ++r) s[r] = rsqrtf(wave_sum(s[r], lane) * (1.0f / D) + EPS);
; #pragma unroll
;         for (int r = 0; r < 8; ++r) {
;             f32x4* dst = (f32x4*)(F.out + O_Y + (size_t)(m0 + r) * D) + lane;
; #pragma unroll
;             for (int jj = 0; jj < 4; ++jj) dst[64 * jj] = unpack4(pk[r][jj]) * s[r] * g[jj];
;         }
	v_pk_add_f32 v[184:185], v[184:185], v[186:187]
	s_nop 0
	v_pk_fma_f32 v[184:185], v[184:185], s[10:11], v[38:39] op_sel_hi:[1,0,0]
	s_nop 0
	v_mul_f32_e32 v42, 0x4b800000, v185
	v_cmp_gt_f32_e64 s[0:1], s29, v185
	v_cmp_gt_f32_e32 vcc, s29, v184
	s_nop 0
	v_cndmask_b32_e64 v42, v185, v42, s[0:1]
	v_rsq_f32_e32 v42, v42
	s_nop 0
	v_mul_f32_e32 v60, 0x45800000, v42
	v_cndmask_b32_e64 v152, v42, v60, s[0:1]
	v_mul_f32_e32 v42, 0x4b800000, v184
	v_cndmask_b32_e32 v42, v184, v42, vcc
	s_lshl_b64 s[0:1], s[12:13], 12
	v_rsq_f32_e32 v42, v42
	v_lshl_add_u64 v[184:185], v[36:37], 0, s[0:1]
	global_store_dwordx4 v[184:185], v[54:57], off nt
	s_lshl_b64 s[0:1], s[14:15], 12
	v_mul_f32_e32 v60, 0x45800000, v42
	v_mov_b32_e32 v54, v46
	v_mov_b32_e32 v55, v48
	v_mov_b32_e32 v48, v47
	v_pk_mul_f32 v[54:55], v[44:45], v[54:55] op_sel_hi:[0,1]
	v_pk_mul_f32 v[46:47], v[44:45], v[48:49] op_sel_hi:[0,1]
	v_pk_mul_f32 v[48:49], v[10:11], v[46:47]
	v_pk_mul_f32 v[46:47], v[8:9], v[54:55]
	global_store_dwordx4 v[184:185], v[46:49], off offset:1024 nt
	v_cndmask_b32_e32 v170, v42, v60, vcc
	v_mov_b32_e32 v42, v45
	v_pk_mul_f32 v[46:47], v[44:45], v[50:51] op_sel_hi:[0,1]
	v_pk_mul_f32 v[48:49], v[44:45], v[52:53] op_sel_hi:[0,1]
	v_pk_mul_f32 v[48:49], v[6:7], v[48:49]
	v_pk_mul_f32 v[46:47], v[4:5], v[46:47]
	global_store_dwordx4 v[184:185], v[46:49], off offset:2048 nt
	v_mov_b32_e32 v60, v63
	v_cmp_lt_i32_e32 vcc, s27, v196
	v_pk_mul_f32 v[46:47], v[44:45], v[42:43] op_sel_hi:[0,1]
	v_pk_mul_f32 v[42:43], v[2:3], v[40:41]
	v_pk_mul_f32 v[40:41], v[0:1], v[46:47]
	global_store_dwordx4 v[184:185], v[40:43], off offset:3072 nt
	v_lshl_add_u64 v[44:45], v[36:37], 0, s[0:1]
	s_lshl_b64 s[0:1], s[16:17], 12
	v_pk_mul_f32 v[40:41], v[62:63], v[72:73] op_sel_hi:[0,1]
	v_pk_mul_f32 v[42:43], v[62:63], v[74:75] op_sel_hi:[0,1]
	v_pk_mul_f32 v[42:43], v[14:15], v[42:43]
	v_pk_mul_f32 v[40:41], v[12:13], v[40:41]
	global_store_dwordx4 v[44:45], v[40:43], off nt
	s_and_b64 vcc, exec, vcc
	s_nop 0
	v_mov_b32_e32 v40, v64
	v_mov_b32_e32 v41, v66
	v_mov_b32_e32 v66, v65
	v_pk_mul_f32 v[40:41], v[62:63], v[40:41] op_sel_hi:[0,1]
	v_pk_mul_f32 v[42:43], v[62:63], v[66:67] op_sel_hi:[0,1]
	v_pk_mul_f32 v[42:43], v[10:11], v[42:43]
	v_pk_mul_f32 v[40:41], v[8:9], v[40:41]
	global_store_dwordx4 v[44:45], v[40:43], off offset:1024 nt
	s_nop 1
	v_pk_mul_f32 v[40:41], v[62:63], v[68:69] op_sel_hi:[0,1]
	v_pk_mul_f32 v[42:43], v[62:63], v[70:71] op_sel_hi:[0,1]
	v_pk_mul_f32 v[42:43], v[6:7], v[42:43]
	v_pk_mul_f32 v[40:41], v[4:5], v[40:41]
	global_store_dwordx4 v[44:45], v[40:43], off offset:2048 nt
	s_nop 1
	v_pk_mul_f32 v[40:41], v[62:63], v[60:61] op_sel_hi:[0,1]
	v_pk_mul_f32 v[42:43], v[62:63], v[58:59] op_sel_hi:[0,1]
	v_pk_mul_f32 v[42:43], v[2:3], v[42:43]
	v_pk_mul_f32 v[40:41], v[0:1], v[40:41]
	global_store_dwordx4 v[44:45], v[40:43], off offset:3072 nt
	v_lshl_add_u64 v[44:45], v[36:37], 0, s[0:1]
	s_lshl_b64 s[0:1], s[18:19], 12
	v_pk_mul_f32 v[40:41], v[80:81], v[90:91] op_sel_hi:[0,1]
	v_pk_mul_f32 v[42:43], v[80:81], v[92:93] op_sel_hi:[0,1]
	v_pk_mul_f32 v[42:43], v[14:15], v[42:43]
	v_pk_mul_f32 v[40:41], v[12:13], v[40:41]
	global_store_dwordx4 v[44:45], v[40:43], off nt
	s_nop 1
	v_mov_b32_e32 v40, v82
	v_mov_b32_e32 v41, v84
	v_mov_b32_e32 v84, v83
	v_pk_mul_f32 v[40:41], v[80:81], v[40:41] op_sel_hi:[0,1]
	v_pk_mul_f32 v[42:43], v[80:81], v[84:85] op_sel_hi:[0,1]
	v_pk_mul_f32 v[42:43], v[10:11], v[42:43]
	v_pk_mul_f32 v[40:41], v[8:9], v[40:41]
	global_store_dwordx4 v[44:45], v[40:43], off offset:1024 nt
	s_nop 1
	v_pk_mul_f32 v[40:41], v[80:81], v[86:87] op_sel_hi:[0,1]
	v_pk_mul_f32 v[42:43], v[80:81], v[88:89] op_sel_hi:[0,1]
	v_pk_mul_f32 v[42:43], v[6:7], v[42:43]
	v_pk_mul_f32 v[40:41], v[4:5], v[40:41]
	global_store_dwordx4 v[44:45], v[40:43], off offset:2048 nt
	s_nop 1
	v_pk_mul_f32 v[40:41], v[80:81], v[78:79] op_sel_hi:[0,1]
	v_pk_mul_f32 v[42:43], v[80:81], v[76:77] op_sel_hi:[0,1]
	v_pk_mul_f32 v[42:43], v[2:3], v[42:43]
	v_pk_mul_f32 v[40:41], v[0:1], v[40:41]
	global_store_dwordx4 v[44:45], v[40:43], off offset:3072 nt
	v_lshl_add_u64 v[44:45], v[36:37], 0, s[0:1]
	s_lshl_b64 s[0:1], s[20:21], 12
	v_pk_mul_f32 v[40:41], v[98:99], v[108:109] op_sel_hi:[0,1]
	v_pk_mul_f32 v[42:43], v[98:99], v[110:111] op_sel_hi:[0,1]
	v_pk_mul_f32 v[42:43], v[14:15], v[42:43]
	v_pk_mul_f32 v[40:41], v[12:13], v[40:41]
	global_store_dwordx4 v[44:45], v[40:43], off nt
	s_nop 1
	v_mov_b32_e32 v40, v100
	v_mov_b32_e32 v41, v102
	v_mov_b32_e32 v102, v101
	v_pk_mul_f32 v[40:41], v[98:99], v[40:41] op_sel_hi:[0,1]
	v_pk_mul_f32 v[42:43], v[98:99], v[102:103] op_sel_hi:[0,1]
	v_pk_mul_f32 v[42:43], v[10:11], v[42:43]
	v_pk_mul_f32 v[40:41], v[8:9], v[40:41]
	global_store_dwordx4 v[44:45], v[40:43], off offset:1024 nt
	s_nop 1
	v_pk_mul_f32 v[40:41], v[98:99], v[104:105] op_sel_hi:[0,1]
	v_pk_mul_f32 v[42:43], v[98:99], v[106:107] op_sel_hi:[0,1]
	v_pk_mul_f32 v[42:43], v[6:7], v[42:43]
	v_pk_mul_f32 v[40:41], v[4:5], v[40:41]
	global_store_dwordx4 v[44:45], v[40:43], off offset:2048 nt
	s_nop 1
	v_pk_mul_f32 v[40:41], v[98:99], v[96:97] op_sel_hi:[0,1]
	v_pk_mul_f32 v[42:43], v[98:99], v[94:95] op_sel_hi:[0,1]
	v_pk_mul_f32 v[42:43], v[2:3], v[42:43]
	v_pk_mul_f32 v[40:41], v[0:1], v[40:41]
	global_store_dwordx4 v[44:45], v[40:43], off offset:3072 nt
	v_lshl_add_u64 v[44:45], v[36:37], 0, s[0:1]
	s_lshl_b64 s[0:1], s[22:23], 12
	v_pk_mul_f32 v[40:41], v[116:117], v[126:127] op_sel_hi:[0,1]
	v_pk_mul_f32 v[42:43], v[116:117], v[128:129] op_sel_hi:[0,1]
	v_pk_mul_f32 v[42:43], v[14:15], v[42:43]
	v_pk_mul_f32 v[40:41], v[12:13], v[40:41]
	global_store_dwordx4 v[44:45], v[40:43], off nt
; __device__ __forceinline__ f32x4 unpack4(u32x2 w) { return (f32x4){bflo(w.x), bfhi(w.x), bflo(w.y), bfhi(w.y)}; }
; __device__ __forceinline__ void final_norm(Frame& F0) {
;     ...
; #pragma unroll
;         for (int r = 0; r < 8; ++r) {
;             f32x4* dst = (f32x4*)(F.out + O_Y + (size_t)(m0 + r) * D) + lane;
; #pragma unroll
;             for (int jj = 0; jj < 4; ++jj) dst[64 * jj] = unpack4(pk[r][jj]) * s[r] * g[jj];
;         }
;     }
	s_nop 1
	v_mov_b32_e32 v40, v118
	v_mov_b32_e32 v41, v120
	v_mov_b32_e32 v120, v119
	v_pk_mul_f32 v[40:41], v[116:117], v[40:41] op_sel_hi:[0,1]
	v_pk_mul_f32 v[42:43], v[116:117], v[120:121] op_sel_hi:[0,1]
	v_pk_mul_f32 v[42:43], v[10:11], v[42:43]
	v_pk_mul_f32 v[40:41], v[8:9], v[40:41]
	global_store_dwordx4 v[44:45], v[40:43], off offset:1024 nt
	s_nop 1
	v_pk_mul_f32 v[40:41], v[116:117], v[122:123] op_sel_hi:[0,1]
	v_pk_mul_f32 v[42:43], v[116:117], v[124:125] op_sel_hi:[0,1]
	v_pk_mul_f32 v[42:43], v[6:7], v[42:43]
	v_pk_mul_f32 v[40:41], v[4:5], v[40:41]
	global_store_dwordx4 v[44:45], v[40:43], off offset:2048 nt
	s_nop 1
	v_pk_mul_f32 v[40:41], v[116:117], v[114:115] op_sel_hi:[0,1]
	v_pk_mul_f32 v[42:43], v[116:117], v[112:113] op_sel_hi:[0,1]
	v_pk_mul_f32 v[42:43], v[2:3], v[42:43]
	v_pk_mul_f32 v[40:41], v[0:1], v[40:41]
	global_store_dwordx4 v[44:45], v[40:43], off offset:3072 nt
	v_lshl_add_u64 v[44:45], v[36:37], 0, s[0:1]
	s_lshl_b64 s[0:1], s[24:25], 12
	v_pk_mul_f32 v[40:41], v[134:135], v[144:145] op_sel_hi:[0,1]
	v_pk_mul_f32 v[42:43], v[134:135], v[146:147] op_sel_hi:[0,1]
	v_pk_mul_f32 v[42:43], v[14:15], v[42:43]
	v_pk_mul_f32 v[40:41], v[12:13], v[40:41]
	global_store_dwordx4 v[44:45], v[40:43], off nt
	s_nop 1
	v_mov_b32_e32 v40, v136
	v_mov_b32_e32 v41, v138
	v_mov_b32_e32 v138, v137
	v_pk_mul_f32 v[40:41], v[134:135], v[40:41] op_sel_hi:[0,1]
	v_pk_mul_f32 v[42:43], v[134:135], v[138:139] op_sel_hi:[0,1]
	v_pk_mul_f32 v[42:43], v[10:11], v[42:43]
	v_pk_mul_f32 v[40:41], v[8:9], v[40:41]
	global_store_dwordx4 v[44:45], v[40:43], off offset:1024 nt
	s_nop 1
	v_pk_mul_f32 v[40:41], v[134:135], v[140:141] op_sel_hi:[0,1]
	v_pk_mul_f32 v[42:43], v[134:135], v[142:143] op_sel_hi:[0,1]
	v_pk_mul_f32 v[42:43], v[6:7], v[42:43]
	v_pk_mul_f32 v[40:41], v[4:5], v[40:41]
	global_store_dwordx4 v[44:45], v[40:43], off offset:2048 nt
	s_nop 1
	v_pk_mul_f32 v[40:41], v[134:135], v[132:133] op_sel_hi:[0,1]
	v_pk_mul_f32 v[42:43], v[134:135], v[130:131] op_sel_hi:[0,1]
	v_pk_mul_f32 v[42:43], v[2:3], v[42:43]
	v_pk_mul_f32 v[40:41], v[0:1], v[40:41]
	global_store_dwordx4 v[44:45], v[40:43], off offset:3072 nt
	v_lshl_add_u64 v[44:45], v[36:37], 0, s[0:1]
	s_lshl_b64 s[0:1], s[8:9], 12
	v_pk_mul_f32 v[40:41], v[152:153], v[162:163] op_sel_hi:[0,1]
	v_pk_mul_f32 v[42:43], v[152:153], v[164:165] op_sel_hi:[0,1]
	v_pk_mul_f32 v[42:43], v[14:15], v[42:43]
	v_pk_mul_f32 v[40:41], v[12:13], v[40:41]
	global_store_dwordx4 v[44:45], v[40:43], off nt
	s_add_i32 s8, s8, s28
	s_nop 0
	v_mov_b32_e32 v40, v154
	v_mov_b32_e32 v41, v156
	v_mov_b32_e32 v156, v155
	v_pk_mul_f32 v[40:41], v[152:153], v[40:41] op_sel_hi:[0,1]
	v_pk_mul_f32 v[42:43], v[152:153], v[156:157] op_sel_hi:[0,1]
	v_pk_mul_f32 v[42:43], v[10:11], v[42:43]
	v_pk_mul_f32 v[40:41], v[8:9], v[40:41]
	global_store_dwordx4 v[44:45], v[40:43], off offset:1024 nt
	s_nop 1
	v_pk_mul_f32 v[40:41], v[152:153], v[158:159] op_sel_hi:[0,1]
	v_pk_mul_f32 v[42:43], v[152:153], v[160:161] op_sel_hi:[0,1]
	v_pk_mul_f32 v[42:43], v[6:7], v[42:43]
	v_pk_mul_f32 v[40:41], v[4:5], v[40:41]
	global_store_dwordx4 v[44:45], v[40:43], off offset:2048 nt
	s_nop 1
	v_pk_mul_f32 v[40:41], v[152:153], v[150:151] op_sel_hi:[0,1]
	v_pk_mul_f32 v[42:43], v[152:153], v[148:149] op_sel_hi:[0,1]
	v_pk_mul_f32 v[42:43], v[2:3], v[42:43]
	v_pk_mul_f32 v[40:41], v[0:1], v[40:41]
	global_store_dwordx4 v[44:45], v[40:43], off offset:3072 nt
	v_lshl_add_u64 v[44:45], v[36:37], 0, s[0:1]
	s_nop 0
	v_pk_mul_f32 v[40:41], v[170:171], v[180:181] op_sel_hi:[0,1]
	v_pk_mul_f32 v[42:43], v[170:171], v[182:183] op_sel_hi:[0,1]
	v_pk_mul_f32 v[42:43], v[14:15], v[42:43]
	v_pk_mul_f32 v[40:41], v[12:13], v[40:41]
	global_store_dwordx4 v[44:45], v[40:43], off nt
	s_nop 1
	v_mov_b32_e32 v40, v172
	v_mov_b32_e32 v41, v174
	v_mov_b32_e32 v174, v173
	v_pk_mul_f32 v[40:41], v[170:171], v[40:41] op_sel_hi:[0,1]
	v_pk_mul_f32 v[42:43], v[170:171], v[174:175] op_sel_hi:[0,1]
	v_pk_mul_f32 v[42:43], v[10:11], v[42:43]
	v_pk_mul_f32 v[40:41], v[8:9], v[40:41]
	global_store_dwordx4 v[44:45], v[40:43], off offset:1024 nt
	s_nop 1
	v_pk_mul_f32 v[40:41], v[170:171], v[176:177] op_sel_hi:[0,1]
	v_pk_mul_f32 v[42:43], v[170:171], v[178:179] op_sel_hi:[0,1]
	v_pk_mul_f32 v[42:43], v[6:7], v[42:43]
	v_pk_mul_f32 v[40:41], v[4:5], v[40:41]
	global_store_dwordx4 v[44:45], v[40:43], off offset:2048 nt
	s_nop 1
	v_pk_mul_f32 v[40:41], v[170:171], v[168:169] op_sel_hi:[0,1]
	v_pk_mul_f32 v[42:43], v[170:171], v[166:167] op_sel_hi:[0,1]
	v_pk_mul_f32 v[42:43], v[2:3], v[42:43]
	v_pk_mul_f32 v[40:41], v[0:1], v[40:41]
	global_store_dwordx4 v[44:45], v[40:43], off offset:3072 nt
	s_cbranch_vccz .LBB0_2365
; __device__ __forceinline__ float dot4(f32x4 a, f32x4 b) { return (a[0] * b[0] + a[1] * b[1]) + (a[2] * b[2] + a[3] * b[3]); }
; __device__ __forceinline__ void final_norm(Frame& F0) {
;     ...
;     if (has_s) {
;         float s = 0.f;
; #pragma unroll
;         for (int jj = 0; jj < 4; ++jj) s += dot4(sv[jj], sv[jj]);
;         const float rs = rsqrtf(wave_sum(s, lane) * (1.0f / D) + EPS);
;         f32x4* dst = (f32x4*)(F.out + O_YS + (size_t)(16 * F.xq + gwx) * D) + lane;
; #pragma unroll
;         for (int jj = 0; jj < 4; ++jj) dst[64 * jj] = sv[jj] * rs * g[jj];
;     }
.LBB0_2366:
	s_andn2_b64 vcc, exec, s[6:7]
	s_cbranch_vccnz .LBB0_2368
	s_waitcnt vmcnt(1)
	v_pk_mul_f32 v[34:35], v[30:31], v[30:31]
	v_pk_mul_f32 v[36:37], v[28:29], v[28:29]
	s_mov_b32 s0, 0x800000
	v_pk_mov_b32 v[38:39], v[36:37], v[34:35] op_sel:[1,0]
	v_mov_b32_e32 v37, v35
	v_pk_add_f32 v[34:35], v[38:39], v[36:37]
	v_pk_mul_f32 v[36:37], v[26:27], v[26:27]
	v_pk_mul_f32 v[38:39], v[24:25], v[24:25]
	v_pk_add_f32 v[34:35], v[34:35], v[34:35] op_sel:[0,1] op_sel_hi:[1,0]
	v_pk_mov_b32 v[40:41], v[38:39], v[36:37] op_sel:[1,0]
	v_mov_b32_e32 v39, v37
	v_pk_add_f32 v[36:37], v[40:41], v[38:39]
	s_waitcnt vmcnt(0)
	v_mul_f32_e32 v38, v16, v16
	v_mul_f32_e32 v39, v17, v17
	v_pk_add_f32 v[36:37], v[36:37], v[36:37] op_sel:[0,1] op_sel_hi:[1,0]
	v_mov_b32_e32 v35, v38
	v_mov_b32_e32 v37, v39
	v_pk_add_f32 v[34:35], v[34:35], v[36:37]
	v_mul_f32_e32 v36, v21, v21
	v_mul_f32_e32 v38, v23, v23
	v_mul_f32_e32 v40, v18, v18
	v_mul_f32_e32 v41, v19, v19
	v_pk_fma_f32 v[36:37], v[20:21], v[20:21], v[36:37] op_sel_hi:[1,1,0]
	v_pk_fma_f32 v[38:39], v[22:23], v[22:23], v[38:39] op_sel_hi:[1,1,0]
	v_mov_b32_e32 v37, v40
	v_mov_b32_e32 v39, v41
	v_pk_add_f32 v[36:37], v[36:37], v[38:39]
	s_nop 0
	v_pk_add_f32 v[34:35], v[34:35], v[36:37]
	s_nop 0
	v_add_f32_e32 v34, v34, v35
	v_xor_b32_e32 v35, 4, v188
	ds_bpermute_b32 v35, v35, v34
	s_waitcnt lgkmcnt(0)
	v_add_f32_e32 v34, v34, v35
	v_xor_b32_e32 v35, 8, v188
	ds_bpermute_b32 v35, v35, v34
	s_waitcnt lgkmcnt(0)
	v_add_f32_e32 v34, v34, v35
	v_xor_b32_e32 v35, 16, v188
	ds_bpermute_b32 v35, v35, v34
	s_waitcnt lgkmcnt(0)
	v_add_f32_e32 v34, v34, v35
	v_xor_b32_e32 v35, 32, v188
	ds_bpermute_b32 v35, v35, v34
	s_waitcnt lgkmcnt(0)
	v_add_f32_e32 v34, v34, v35
	v_xor_b32_e32 v35, 64, v188
	ds_bpermute_b32 v35, v35, v34
	s_waitcnt lgkmcnt(0)
	v_add_f32_e32 v34, v34, v35
	v_xor_b32_e32 v35, 0x80, v188
	ds_bpermute_b32 v35, v35, v34
	s_waitcnt lgkmcnt(0)
	v_add_f32_e32 v34, v34, v35
	v_mov_b32_e32 v35, 0x358637bd
	v_fmac_f32_e32 v35, 0x3a800000, v34
	v_mul_f32_e32 v34, 0x4b800000, v35
	v_cmp_gt_f32_e32 vcc, s0, v35
	s_lshl_b32 s0, s26, 4
	s_add_i32 s0, s0, s11
	v_cndmask_b32_e32 v34, v35, v34, vcc
	v_rsq_f32_e32 v34, v34
	s_ashr_i32 s1, s0, 31
	s_lshl_b64 s[0:1], s[0:1], 12
	s_add_u32 s0, s4, s0
	v_mul_f32_e32 v35, 0x45800000, v34
	s_addc_u32 s1, s5, s1
	v_cndmask_b32_e32 v34, v34, v35, vcc
	v_lshl_add_u64 v[32:33], v[32:33], 4, s[0:1]
	s_mov_b64 s[0:1], 0x4000000
	v_lshl_add_u64 v[36:37], v[32:33], 0, s[0:1]
	v_pk_mul_f32 v[28:29], v[28:29], v[34:35] op_sel_hi:[1,0]
	s_brev_b32 s0, 32
	v_pk_mul_f32 v[30:31], v[30:31], v[34:35] op_sel_hi:[1,0]
	v_pk_mul_f32 v[12:13], v[12:13], v[28:29]
	v_add_co_u32_e32 v28, vcc, s0, v32
	v_pk_mul_f32 v[14:15], v[14:15], v[30:31]
	s_nop 0
	v_addc_co_u32_e32 v29, vcc, 0, v33, vcc
	global_store_dwordx4 v[28:29], v[12:15], off nt
	s_nop 1
	v_pk_mul_f32 v[12:13], v[24:25], v[34:35] op_sel_hi:[1,0]
	v_pk_mul_f32 v[14:15], v[26:27], v[34:35] op_sel_hi:[1,0]
	v_pk_mul_f32 v[8:9], v[8:9], v[12:13]
	v_pk_mul_f32 v[10:11], v[10:11], v[14:15]
	global_store_dwordx4 v[36:37], v[8:11], off offset:1024 nt
	s_nop 1
	v_pk_mul_f32 v[8:9], v[20:21], v[34:35] op_sel_hi:[1,0]
	v_pk_mul_f32 v[10:11], v[22:23], v[34:35] op_sel_hi:[1,0]
	v_pk_mul_f32 v[4:5], v[4:5], v[8:9]
	v_pk_mul_f32 v[6:7], v[6:7], v[10:11]
	global_store_dwordx4 v[36:37], v[4:7], off offset:2048 nt
	s_nop 1
	v_pk_mul_f32 v[4:5], v[16:17], v[34:35] op_sel_hi:[1,0]
	v_pk_mul_f32 v[6:7], v[18:19], v[34:35] op_sel_hi:[1,0]
	v_pk_mul_f32 v[0:1], v[0:1], v[4:5]
	v_pk_mul_f32 v[2:3], v[2:3], v[6:7]
	global_store_dwordx4 v[36:37], v[0:3], off offset:3072 nt
